# p2 row items: second-half loads issued with the first-half batch (before its stores); second half has no memory wait and no store drain
# speedup vs baseline: 1.0075x; 1.0044x over previous
; DEVI void mixab_row4(const Params& P, int l, int base, int lt0, int tid) {
;     ...
;   {
;     float pk[6][4], ab[4][4], wa[3][4];
; #pragma unroll
;     for (int k = 0; k < 6; ++k) {
;       const int tt = t0 - 2 + k;
;       if (tt >= 0) {
;         const bfu* zr = z + (long)(lt0 - 2 + k) * NCOL;
;         float ac[4], ax[4];
;         load4bf(zr + 1024 + c, ac); load4bf(zr + 2048 + c, ax);
; #pragma unroll
;         for (int i = 0; i < 4; ++i) pk[k][i] = ac[i] * ax[i];
;       } else if (ti.sample) {
;         ld4f(P.in[2] + ((long)(l * 8 + ti.seq) * 2 + (tt + 2)) * 1024 + c, pk[k]);
;       } else {
; #pragma unroll
;         for (int i = 0; i < 4; ++i) pk[k][i] = 0.f;
;       }
;     }
; #pragma unroll
;     for (int r = 0; r < 4; ++r) load4bf(z + (long)(lt0 + r) * NCOL + c, ab[r]);
; #pragma unroll
;     for (int k = 0; k < 3; ++k) ld4f(P.in[8] + (long)(l * 3 + k) * 1024 + c, wa[k]);
; #pragma unroll
;     for (int r = 0; r < 4; ++r) {
;       float o[4];
; #pragma unroll
;       for (int i = 0; i < 4; ++i) o[i] = ab[r][i] * (wa[0][i] * pk[r][i] + wa[1][i] * pk[r + 1][i] + wa[2][i] * pk[r + 2][i]);
;       store4bf((bfu*)(P.ws + O_UA) + (long)(lt0 + r) * 1024 + c, o);
;     ...
; #pragma unroll
;     for (int k = 0; k < 7; ++k) {
;       const int tt = t0 - 3 + k;
;       if (tt >= 0) {
;         load4bf(z + (long)(lt0 - 3 + k) * NCOL + 3072 + c, xk[k]);
;       } else if (ti.sample) {
;         ld4f(P.in[3] + ((long)(l * 8 + ti.seq) * 3 + (tt + 3)) * 1024 + c, xk[k]);
;       } else {
; #pragma unroll
;         for (int i = 0; i < 4; ++i) xk[k][i] = 0.f;
;       }
;     }
; #pragma unroll
;     for (int k = 0; k < 4; ++k) ld4f(P.in[9] + (long)(l * 4 + k) * 1024 + c, wb[k]);
;     ld4f(P.in[10] + (long)l * 1024 + c, bb);
.LBB0_361:
	v_mad_i64_i32 v[0:1], s[52:53], s48, v191, v[74:75]
	v_lshl_add_u64 v[0:1], v[0:1], 0, v[104:105]
	s_movk_i32 s4, 0x1000
	s_or_b32 s52, s48, 1
	v_add_co_u32_e32 v4, vcc, s4, v0
	v_mad_i64_i32 v[8:9], s[56:57], s52, v191, v[74:75]
	s_nop 0
	v_addc_co_u32_e32 v5, vcc, 0, v1, vcc
	v_mov_b32_e32 v198, v4
	v_mov_b32_e32 v199, v5
	v_lshl_add_u64 v[8:9], v[8:9], 0, v[104:105]
	v_add_co_u32_e32 v16, vcc, s4, v8
	s_or_b32 s60, s48, 2
	global_load_dwordx2 v[10:11], v[0:1], off offset:2048
	s_nop 0
	global_load_dwordx2 v[4:5], v[4:5], off
	s_nop 0
	global_load_dwordx2 v[12:13], v[8:9], off offset:2048
	v_addc_co_u32_e32 v17, vcc, 0, v9, vcc
	v_mad_i64_i32 v[8:9], s[56:57], s60, v191, v[74:75]
	s_or_b32 s62, s48, 3
	v_lshl_add_u64 v[8:9], v[8:9], 0, v[104:105]
	v_mad_i64_i32 v[18:19], s[56:57], s62, v191, v[74:75]
	v_lshl_add_u64 v[20:21], v[18:19], 0, v[104:105]
	v_add_co_u32_e32 v18, vcc, s4, v8
	global_load_dwordx2 v[14:15], v[8:9], off offset:2048
	s_nop 0
	v_addc_co_u32_e32 v19, vcc, 0, v9, vcc
	global_load_dwordx2 v[38:39], v[20:21], off offset:2048
	global_load_dwordx2 v[40:41], v[16:17], off
	v_add_co_u32_e32 v20, vcc, s4, v20
	v_mad_i64_i32 v[26:27], s[56:57], s62, v191, v[106:107]
	s_nop 0
	v_addc_co_u32_e32 v21, vcc, 0, v21, vcc
	global_load_dwordx2 v[8:9], v[18:19], off
	global_load_dwordx2 v[42:43], v[20:21], off
	global_load_dwordx2 v[44:45], v[26:27], off
	v_mad_i64_i32 v[26:27], s[56:57], s60, v191, v[106:107]
	global_load_dwordx2 v[46:47], v[26:27], off
	v_mad_i64_i32 v[26:27], s[56:57], s52, v191, v[106:107]
	v_mad_i64_i32 v[34:35], s[56:57], s48, v191, v[106:107]
	global_load_dwordx2 v[48:49], v[26:27], off
	s_nop 0
	global_load_dwordx4 v[26:29], v[108:109], off
	global_load_dwordx4 v[30:33], v[112:113], off
	global_load_dwordx2 v[50:51], v[34:35], off
	s_nop 0
	global_load_dwordx4 v[34:37], v[110:111], off
	global_load_dwordx2 v[226:227], v[16:17], off offset:2048
	global_load_dwordx2 v[228:229], v[198:199], off offset:2048
	global_load_dwordx2 v[222:223], v[18:19], off offset:2048
	global_load_dwordx2 v[224:225], v[20:21], off offset:2048
	global_load_dwordx4 v[232:235], v[118:119], off
	global_load_dwordx4 v[236:239], v[120:121], off
	global_load_dwordx4 v[240:243], v[122:123], off
	global_load_dwordx4 v[244:247], v[124:125], off
	global_load_dwordx4 v[248:251], v[126:127], off
	s_ashr_i32 s49, s48, 31
	s_lshl_b64 s[56:57], s[48:49], 11
	s_ashr_i32 s53, s52, 31
	s_lshl_b64 s[58:59], s[52:53], 11
	s_ashr_i32 s61, s60, 31
	s_lshl_b64 s[60:61], s[60:61], 11
	s_ashr_i32 s63, s62, 31
	s_lshl_b64 s[62:63], s[62:63], 11
	s_and_b64 s[52:53], s[26:27], exec
	s_cselect_b32 s47, 0xffc, 28
	s_cmp_eq_u32 s64, s47
	s_cselect_b64 s[52:53], -1, 0
	s_cmp_lg_u32 s64, s47
	s_waitcnt vmcnt(23)
	v_lshlrev_b32_e32 v52, 16, v10
	v_lshlrev_b32_e32 v53, 16, v11
	s_waitcnt vmcnt(21)
	v_lshlrev_b32_e32 v58, 16, v12
	v_lshlrev_b32_e32 v59, 16, v13
	v_lshlrev_b32_e32 v56, 16, v4
	v_lshlrev_b32_e32 v57, 16, v5
	v_and_b32_e32 v55, 0xffff0000, v11
	v_and_b32_e32 v54, 0xffff0000, v10
	v_and_b32_e32 v5, 0xffff0000, v5
	v_and_b32_e32 v4, 0xffff0000, v4
	v_pk_mul_f32 v[52:53], v[52:53], v[56:57]
	v_pk_mul_f32 v[4:5], v[54:55], v[4:5]
	v_and_b32_e32 v61, 0xffff0000, v13
	v_and_b32_e32 v60, 0xffff0000, v12
	s_waitcnt vmcnt(20)
	v_lshlrev_b32_e32 v10, 16, v14
	v_and_b32_e32 v11, 0xffff0000, v14
	v_lshlrev_b32_e32 v12, 16, v15
	s_waitcnt vmcnt(18)
	v_lshlrev_b32_e32 v62, 16, v40
	v_lshlrev_b32_e32 v63, 16, v41
	v_pk_mul_f32 v[58:59], v[58:59], v[62:63]
	v_and_b32_e32 v13, 0xffff0000, v15
	v_lshlrev_b32_e32 v14, 16, v38
	v_and_b32_e32 v15, 0xffff0000, v38
	v_lshlrev_b32_e32 v38, 16, v39
	s_waitcnt vmcnt(17)
	v_lshlrev_b32_e32 v170, 16, v8
	v_and_b32_e32 v171, 0xffff0000, v8
	v_lshlrev_b32_e32 v172, 16, v9
	v_and_b32_e32 v173, 0xffff0000, v9
	v_pk_mul_f32 v[8:9], v[10:11], v[170:171]
	v_pk_mul_f32 v[10:11], v[12:13], v[172:173]
	v_and_b32_e32 v39, 0xffff0000, v39
	s_waitcnt vmcnt(16)
	v_lshlrev_b32_e32 v12, 16, v42
	v_and_b32_e32 v13, 0xffff0000, v42
	s_waitcnt vmcnt(12)
	v_mov_b32_e32 v62, v26
	v_mov_b32_e32 v63, v28
	s_waitcnt vmcnt(11)
	v_mov_b32_e32 v174, v30
	v_mov_b32_e32 v175, v32
	v_mov_b32_e32 v28, v27
	v_mov_b32_e32 v32, v31
	s_waitcnt vmcnt(10)
	v_lshlrev_b32_e32 v27, 16, v51
	v_lshlrev_b32_e32 v26, 16, v50
	v_and_b32_e32 v31, 0xffff0000, v51
	v_and_b32_e32 v30, 0xffff0000, v50
	s_waitcnt vmcnt(0)
; DEVI void mixab_row4(const Params& P, int l, int base, int lt0, int tid) {
;     ...
; #pragma unroll
;     for (int r = 0; r < 4; ++r) load4bf(z + (long)(lt0 + r) * NCOL + c, ab[r]);
; #pragma unroll
;     for (int k = 0; k < 3; ++k) ld4f(P.in[8] + (long)(l * 3 + k) * 1024 + c, wa[k]);
; #pragma unroll
;     for (int r = 0; r < 4; ++r) {
;       float o[4];
; #pragma unroll
;       for (int i = 0; i < 4; ++i) o[i] = ab[r][i] * (wa[0][i] * pk[r][i] + wa[1][i] * pk[r + 1][i] + wa[2][i] * pk[r + 2][i]);
;       store4bf((bfu*)(P.ws + O_UA) + (long)(lt0 + r) * 1024 + c, o);
;     }
;     if (t0 + 4 == T) {
	v_mov_b32_e32 v50, v34
	v_mov_b32_e32 v51, v36
	v_pk_mul_f32 v[176:177], v[24:25], v[50:51]
	v_mov_b32_e32 v36, v35
	v_pk_fma_f32 v[22:23], v[22:23], v[62:63], v[176:177]
	v_pk_mul_f32 v[34:35], v[6:7], v[36:37]
	v_pk_fma_f32 v[22:23], v[52:53], v[174:175], v[22:23]
	v_pk_fma_f32 v[2:3], v[2:3], v[28:29], v[34:35]
	v_pk_mul_f32 v[22:23], v[22:23], v[26:27]
	v_pk_fma_f32 v[2:3], v[4:5], v[32:33], v[2:3]
	v_and_b32_sdwa v26, v23, v95 dst_sel:DWORD dst_unused:UNUSED_PAD src0_sel:WORD_1 src1_sel:DWORD
	v_pk_mul_f32 v[2:3], v[2:3], v[30:31]
	v_and_b32_sdwa v27, v22, v95 dst_sel:DWORD dst_unused:UNUSED_PAD src0_sel:WORD_1 src1_sel:DWORD
	v_add3_u32 v22, v22, v27, s39
	v_add3_u32 v23, v23, v26, s39
	v_and_b32_sdwa v26, v3, v95 dst_sel:DWORD dst_unused:UNUSED_PAD src0_sel:WORD_1 src1_sel:DWORD
	v_and_b32_sdwa v27, v2, v95 dst_sel:DWORD dst_unused:UNUSED_PAD src0_sel:WORD_1 src1_sel:DWORD
	v_add3_u32 v3, v3, v26, s39
	v_add3_u32 v2, v2, v27, s39
	v_lshlrev_b32_e32 v42, 16, v43
	v_and_b32_e32 v43, 0xffff0000, v43
	v_and_b32_e32 v3, 0xffff0000, v3
	v_and_b32_e32 v2, 0xffff0000, v2
	v_pk_mul_f32 v[12:13], v[14:15], v[12:13]
	v_pk_mul_f32 v[14:15], v[38:39], v[42:43]
	v_lshl_add_u64 v[38:39], v[114:115], 0, s[56:57]
	v_or_b32_sdwa v3, v3, v23 dst_sel:DWORD dst_unused:UNUSED_PAD src0_sel:DWORD src1_sel:WORD_1
	v_or_b32_sdwa v2, v2, v22 dst_sel:DWORD dst_unused:UNUSED_PAD src0_sel:DWORD src1_sel:WORD_1
	global_store_dwordx2 v[38:39], v[2:3], off
	v_pk_mul_f32 v[2:3], v[52:53], v[50:51]
	v_and_b32_e32 v41, 0xffff0000, v41
	v_and_b32_e32 v40, 0xffff0000, v40
	v_pk_fma_f32 v[2:3], v[24:25], v[62:63], v[2:3]
	v_pk_mul_f32 v[22:23], v[4:5], v[36:37]
	v_pk_mul_f32 v[40:41], v[60:61], v[40:41]
	v_lshlrev_b32_e32 v57, 16, v49
	v_lshlrev_b32_e32 v56, 16, v48
	v_pk_fma_f32 v[2:3], v[58:59], v[174:175], v[2:3]
	v_pk_fma_f32 v[6:7], v[6:7], v[28:29], v[22:23]
	v_and_b32_e32 v49, 0xffff0000, v49
	v_and_b32_e32 v48, 0xffff0000, v48
	v_pk_mul_f32 v[2:3], v[2:3], v[56:57]
	v_pk_fma_f32 v[6:7], v[40:41], v[32:33], v[6:7]
	v_and_b32_sdwa v22, v3, v95 dst_sel:DWORD dst_unused:UNUSED_PAD src0_sel:WORD_1 src1_sel:DWORD
	v_pk_mul_f32 v[6:7], v[6:7], v[48:49]
	v_and_b32_sdwa v23, v2, v95 dst_sel:DWORD dst_unused:UNUSED_PAD src0_sel:WORD_1 src1_sel:DWORD
	v_add3_u32 v2, v2, v23, s39
	v_add3_u32 v3, v3, v22, s39
	v_and_b32_sdwa v22, v7, v95 dst_sel:DWORD dst_unused:UNUSED_PAD src0_sel:WORD_1 src1_sel:DWORD
	v_and_b32_sdwa v23, v6, v95 dst_sel:DWORD dst_unused:UNUSED_PAD src0_sel:WORD_1 src1_sel:DWORD
	v_add3_u32 v7, v7, v22, s39
	v_add3_u32 v6, v6, v23, s39
	v_and_b32_e32 v7, 0xffff0000, v7
	v_and_b32_e32 v6, 0xffff0000, v6
	v_lshl_add_u64 v[42:43], v[114:115], 0, s[58:59]
	v_or_b32_sdwa v3, v7, v3 dst_sel:DWORD dst_unused:UNUSED_PAD src0_sel:DWORD src1_sel:WORD_1
	v_or_b32_sdwa v2, v6, v2 dst_sel:DWORD dst_unused:UNUSED_PAD src0_sel:DWORD src1_sel:WORD_1
	global_store_dwordx2 v[42:43], v[2:3], off
	v_pk_mul_f32 v[2:3], v[58:59], v[50:51]
	v_mov_b32_e32 v6, v8
	v_pk_fma_f32 v[2:3], v[52:53], v[62:63], v[2:3]
	v_mov_b32_e32 v7, v10
	v_pk_mul_f32 v[22:23], v[40:41], v[36:37]
	v_lshlrev_b32_e32 v55, 16, v47
	v_lshlrev_b32_e32 v54, 16, v46
	v_pk_fma_f32 v[2:3], v[6:7], v[174:175], v[2:3]
	v_pk_fma_f32 v[4:5], v[4:5], v[28:29], v[22:23]
	v_mov_b32_e32 v22, v9
	v_mov_b32_e32 v23, v11
	v_and_b32_e32 v47, 0xffff0000, v47
	v_and_b32_e32 v46, 0xffff0000, v46
	v_pk_mul_f32 v[2:3], v[2:3], v[54:55]
	v_pk_fma_f32 v[4:5], v[22:23], v[32:33], v[4:5]
	v_and_b32_sdwa v24, v3, v95 dst_sel:DWORD dst_unused:UNUSED_PAD src0_sel:WORD_1 src1_sel:DWORD
	v_pk_mul_f32 v[4:5], v[4:5], v[46:47]
	v_and_b32_sdwa v25, v2, v95 dst_sel:DWORD dst_unused:UNUSED_PAD src0_sel:WORD_1 src1_sel:DWORD
	v_add3_u32 v2, v2, v25, s39
	v_add3_u32 v3, v3, v24, s39
	v_and_b32_sdwa v24, v5, v95 dst_sel:DWORD dst_unused:UNUSED_PAD src0_sel:WORD_1 src1_sel:DWORD
	v_and_b32_sdwa v25, v4, v95 dst_sel:DWORD dst_unused:UNUSED_PAD src0_sel:WORD_1 src1_sel:DWORD
	v_add3_u32 v5, v5, v24, s39
	v_add3_u32 v4, v4, v25, s39
	v_and_b32_e32 v5, 0xffff0000, v5
	v_and_b32_e32 v4, 0xffff0000, v4
	v_lshl_add_u64 v[170:171], v[114:115], 0, s[60:61]
	v_or_b32_sdwa v3, v5, v3 dst_sel:DWORD dst_unused:UNUSED_PAD src0_sel:DWORD src1_sel:WORD_1
	v_or_b32_sdwa v2, v4, v2 dst_sel:DWORD dst_unused:UNUSED_PAD src0_sel:DWORD src1_sel:WORD_1
	global_store_dwordx2 v[170:171], v[2:3], off
	v_pk_mul_f32 v[2:3], v[6:7], v[50:51]
	v_mov_b32_e32 v4, v12
	v_pk_fma_f32 v[2:3], v[58:59], v[62:63], v[2:3]
	v_mov_b32_e32 v5, v14
	v_pk_fma_f32 v[2:3], v[4:5], v[174:175], v[2:3]
	v_pk_mul_f32 v[4:5], v[22:23], v[36:37]
	v_lshlrev_b32_e32 v61, 16, v45
	v_lshlrev_b32_e32 v60, 16, v44
	v_pk_fma_f32 v[4:5], v[40:41], v[28:29], v[4:5]
	v_mov_b32_e32 v6, v13
	v_mov_b32_e32 v7, v15
	v_and_b32_e32 v45, 0xffff0000, v45
	v_and_b32_e32 v44, 0xffff0000, v44
	v_pk_mul_f32 v[2:3], v[2:3], v[60:61]
	v_pk_fma_f32 v[4:5], v[6:7], v[32:33], v[4:5]
	v_and_b32_sdwa v6, v3, v95 dst_sel:DWORD dst_unused:UNUSED_PAD src0_sel:WORD_1 src1_sel:DWORD
	v_pk_mul_f32 v[4:5], v[4:5], v[44:45]
	v_and_b32_sdwa v7, v2, v95 dst_sel:DWORD dst_unused:UNUSED_PAD src0_sel:WORD_1 src1_sel:DWORD
	v_add3_u32 v2, v2, v7, s39
	v_add3_u32 v3, v3, v6, s39
	v_and_b32_sdwa v6, v5, v95 dst_sel:DWORD dst_unused:UNUSED_PAD src0_sel:WORD_1 src1_sel:DWORD
	v_and_b32_sdwa v7, v4, v95 dst_sel:DWORD dst_unused:UNUSED_PAD src0_sel:WORD_1 src1_sel:DWORD
	v_add3_u32 v5, v5, v6, s39
	v_add3_u32 v4, v4, v7, s39
	v_and_b32_e32 v5, 0xffff0000, v5
	v_and_b32_e32 v4, 0xffff0000, v4
	v_lshl_add_u64 v[172:173], v[114:115], 0, s[62:63]
	v_or_b32_sdwa v3, v5, v3 dst_sel:DWORD dst_unused:UNUSED_PAD src0_sel:DWORD src1_sel:WORD_1
	v_or_b32_sdwa v2, v4, v2 dst_sel:DWORD dst_unused:UNUSED_PAD src0_sel:DWORD src1_sel:WORD_1
	global_store_dwordx2 v[172:173], v[2:3], off
	s_cbranch_scc1 .LBB0_367
	s_and_b64 vcc, exec, s[42:43]
	s_mov_b64 s[66:67], -1
	s_cbranch_vccnz .LBB0_364
	v_readlane_b32 s4, v254, 62
	s_add_u32 s64, s4, s54
	v_readlane_b32 s4, v254, 63
	s_addc_u32 s65, s4, s55
	s_mov_b64 s[66:67], 0

; DEVI void mixab_row4(const Params& P, int l, int base, int lt0, int tid) {
;     ...
;   {
;     float xk[7][4], wb[4][4], bb[4];
; #pragma unroll
;     for (int k = 0; k < 7; ++k) {
;       const int tt = t0 - 3 + k;
;       if (tt >= 0) {
;         load4bf(z + (long)(lt0 - 3 + k) * NCOL + 3072 + c, xk[k]);
;       } else if (ti.sample) {
;         ld4f(P.in[3] + ((long)(l * 8 + ti.seq) * 3 + (tt + 3)) * 1024 + c, xk[k]);
;       } else {
; #pragma unroll
;         for (int i = 0; i < 4; ++i) xk[k][i] = 0.f;
;       }
;     }
; #pragma unroll
;     for (int k = 0; k < 4; ++k) ld4f(P.in[9] + (long)(l * 4 + k) * 1024 + c, wb[k]);
;     ld4f(P.in[10] + (long)l * 1024 + c, bb);
; #pragma unroll
;     for (int r = 0; r < 4; ++r) {
;       float o2[4];
; #pragma unroll
;       for (int i = 0; i < 4; ++i)
;         o2[i] = wb[0][i] * xk[r][i] + wb[1][i] * xk[r + 1][i] + wb[2][i] * xk[r + 2][i] + wb[3][i] * xk[r + 3][i] + bb[i];
;       store4bf((bfu*)(P.ws + O_CB) + (long)(lt0 + r) * 1024 + c, o2);
;     }
.LBB0_382:
	v_mov_b32_e32 v2, v226
	v_mov_b32_e32 v3, v227
	v_mov_b32_e32 v0, v228
	v_mov_b32_e32 v1, v229
	v_mov_b32_e32 v14, v232
	v_mov_b32_e32 v15, v233
	v_mov_b32_e32 v16, v234
	v_mov_b32_e32 v17, v235
	v_mov_b32_e32 v30, v236
	v_mov_b32_e32 v31, v237
	v_mov_b32_e32 v32, v238
	v_mov_b32_e32 v33, v239
	v_mov_b32_e32 v18, v240
	v_mov_b32_e32 v19, v241
	v_mov_b32_e32 v20, v242
	v_mov_b32_e32 v21, v243
	v_mov_b32_e32 v22, v244
	v_mov_b32_e32 v23, v245
	v_mov_b32_e32 v24, v246
	v_mov_b32_e32 v25, v247
	v_mov_b32_e32 v26, v248
	v_mov_b32_e32 v27, v249
	v_mov_b32_e32 v28, v250
	v_mov_b32_e32 v29, v251
	v_lshl_add_u64 v[62:63], v[128:129], 0, s[56:57]
	v_lshl_add_u64 v[48:49], v[128:129], 0, s[58:59]
	v_lshl_add_u64 v[46:47], v[128:129], 0, s[60:61]
	v_lshl_add_u64 v[40:41], v[128:129], 0, s[62:63]
	s_andn2_b64 vcc, exec, s[52:53]
	v_and_b32_e32 v11, 0xffff0000, v3
	v_and_b32_e32 v10, 0xffff0000, v2
	v_lshlrev_b32_e32 v44, 16, v0
	v_lshlrev_b32_e32 v45, 16, v1
	v_and_b32_e32 v43, 0xffff0000, v1
	v_and_b32_e32 v42, 0xffff0000, v0
	v_lshlrev_b32_e32 v0, 16, v2
	v_lshlrev_b32_e32 v1, 16, v3
	v_mov_b32_e32 v2, v222
	v_mov_b32_e32 v3, v223
	v_lshlrev_b32_e32 v37, 16, v3
	v_lshlrev_b32_e32 v36, 16, v2
	v_and_b32_e32 v7, 0xffff0000, v3
	v_and_b32_e32 v6, 0xffff0000, v2
	v_mov_b32_e32 v2, v224
	v_mov_b32_e32 v3, v225
	v_mov_b32_e32 v54, v14
	v_mov_b32_e32 v56, v30
	v_mov_b32_e32 v57, v32
	v_mov_b32_e32 v32, v31
	v_mov_b32_e32 v55, v16
	v_pk_mul_f32 v[58:59], v[50:51], v[56:57]
	v_mov_b32_e32 v16, v15
	v_pk_mul_f32 v[14:15], v[8:9], v[32:33]
	v_pk_fma_f32 v[58:59], v[52:53], v[54:55], v[58:59]
	v_mov_b32_e32 v52, v18
	v_mov_b32_e32 v53, v20
	v_pk_fma_f32 v[12:13], v[12:13], v[16:17], v[14:15]
	v_mov_b32_e32 v20, v19
	v_pk_fma_f32 v[60:61], v[38:39], v[52:53], v[58:59]
	v_mov_b32_e32 v58, v22
	v_mov_b32_e32 v59, v24
	v_pk_fma_f32 v[12:13], v[4:5], v[20:21], v[12:13]
	v_mov_b32_e32 v24, v23
	v_pk_fma_f32 v[170:171], v[58:59], v[44:45], v[60:61]
	v_mov_b32_e32 v61, v28
	v_pk_fma_f32 v[12:13], v[24:25], v[42:43], v[12:13]
	v_mov_b32_e32 v28, v27
	v_mov_b32_e32 v60, v26
	v_pk_add_f32 v[12:13], v[12:13], v[28:29]
	v_pk_add_f32 v[170:171], v[170:171], v[60:61]
	v_and_b32_sdwa v18, v13, v95 dst_sel:DWORD dst_unused:UNUSED_PAD src0_sel:WORD_1 src1_sel:DWORD
	v_and_b32_sdwa v19, v12, v95 dst_sel:DWORD dst_unused:UNUSED_PAD src0_sel:WORD_1 src1_sel:DWORD
	v_and_b32_sdwa v14, v171, v95 dst_sel:DWORD dst_unused:UNUSED_PAD src0_sel:WORD_1 src1_sel:DWORD
	v_and_b32_sdwa v15, v170, v95 dst_sel:DWORD dst_unused:UNUSED_PAD src0_sel:WORD_1 src1_sel:DWORD
	v_add3_u32 v13, v13, v18, s39
	v_add3_u32 v12, v12, v19, s39
	v_add3_u32 v15, v170, v15, s39
	v_add3_u32 v14, v171, v14, s39
	v_and_b32_e32 v13, 0xffff0000, v13
	v_and_b32_e32 v12, 0xffff0000, v12
	v_or_b32_sdwa v13, v13, v14 dst_sel:DWORD dst_unused:UNUSED_PAD src0_sel:DWORD src1_sel:WORD_1
	v_or_b32_sdwa v12, v12, v15 dst_sel:DWORD dst_unused:UNUSED_PAD src0_sel:DWORD src1_sel:WORD_1
	global_store_dwordx2 v[62:63], v[12:13], off
	v_pk_mul_f32 v[12:13], v[38:39], v[56:57]
	v_pk_mul_f32 v[14:15], v[4:5], v[32:33]
	v_pk_fma_f32 v[12:13], v[50:51], v[54:55], v[12:13]
	v_pk_fma_f32 v[8:9], v[8:9], v[16:17], v[14:15]
	v_pk_fma_f32 v[12:13], v[52:53], v[44:45], v[12:13]
	v_pk_fma_f32 v[8:9], v[20:21], v[42:43], v[8:9]
	v_pk_fma_f32 v[12:13], v[58:59], v[0:1], v[12:13]
	v_pk_fma_f32 v[8:9], v[24:25], v[10:11], v[8:9]
	v_pk_add_f32 v[12:13], v[12:13], v[60:61]
	v_pk_add_f32 v[8:9], v[8:9], v[28:29]
	v_and_b32_sdwa v14, v13, v95 dst_sel:DWORD dst_unused:UNUSED_PAD src0_sel:WORD_1 src1_sel:DWORD
	v_and_b32_sdwa v15, v12, v95 dst_sel:DWORD dst_unused:UNUSED_PAD src0_sel:WORD_1 src1_sel:DWORD
	v_add3_u32 v12, v12, v15, s39
	v_add3_u32 v13, v13, v14, s39
	v_and_b32_sdwa v14, v9, v95 dst_sel:DWORD dst_unused:UNUSED_PAD src0_sel:WORD_1 src1_sel:DWORD
	v_and_b32_sdwa v15, v8, v95 dst_sel:DWORD dst_unused:UNUSED_PAD src0_sel:WORD_1 src1_sel:DWORD
	v_add3_u32 v9, v9, v14, s39
	v_add3_u32 v8, v8, v15, s39
	v_and_b32_e32 v9, 0xffff0000, v9
	v_and_b32_e32 v8, 0xffff0000, v8
	v_or_b32_sdwa v9, v9, v13 dst_sel:DWORD dst_unused:UNUSED_PAD src0_sel:DWORD src1_sel:WORD_1
	v_or_b32_sdwa v8, v8, v12 dst_sel:DWORD dst_unused:UNUSED_PAD src0_sel:DWORD src1_sel:WORD_1
	global_store_dwordx2 v[48:49], v[8:9], off
	v_pk_mul_f32 v[8:9], v[56:57], v[44:45]
	v_pk_mul_f32 v[12:13], v[32:33], v[42:43]
	v_pk_fma_f32 v[8:9], v[38:39], v[54:55], v[8:9]
	v_pk_fma_f32 v[4:5], v[4:5], v[16:17], v[12:13]
	v_pk_fma_f32 v[8:9], v[52:53], v[0:1], v[8:9]
	v_pk_fma_f32 v[4:5], v[20:21], v[10:11], v[4:5]
	v_pk_fma_f32 v[8:9], v[58:59], v[36:37], v[8:9]
	v_pk_fma_f32 v[4:5], v[24:25], v[6:7], v[4:5]
	v_pk_add_f32 v[8:9], v[8:9], v[60:61]
	v_pk_add_f32 v[4:5], v[4:5], v[28:29]
	v_and_b32_sdwa v12, v9, v95 dst_sel:DWORD dst_unused:UNUSED_PAD src0_sel:WORD_1 src1_sel:DWORD
	v_and_b32_sdwa v13, v8, v95 dst_sel:DWORD dst_unused:UNUSED_PAD src0_sel:WORD_1 src1_sel:DWORD
	v_add3_u32 v8, v8, v13, s39
	v_add3_u32 v9, v9, v12, s39
	v_and_b32_sdwa v12, v5, v95 dst_sel:DWORD dst_unused:UNUSED_PAD src0_sel:WORD_1 src1_sel:DWORD
	v_and_b32_sdwa v13, v4, v95 dst_sel:DWORD dst_unused:UNUSED_PAD src0_sel:WORD_1 src1_sel:DWORD
	v_add3_u32 v5, v5, v12, s39
	v_add3_u32 v4, v4, v13, s39
	v_and_b32_e32 v5, 0xffff0000, v5
	v_and_b32_e32 v4, 0xffff0000, v4
	v_or_b32_sdwa v5, v5, v9 dst_sel:DWORD dst_unused:UNUSED_PAD src0_sel:DWORD src1_sel:WORD_1
	v_or_b32_sdwa v4, v4, v8 dst_sel:DWORD dst_unused:UNUSED_PAD src0_sel:DWORD src1_sel:WORD_1
	global_store_dwordx2 v[46:47], v[4:5], off
	v_pk_mul_f32 v[4:5], v[56:57], v[0:1]
	v_pk_mul_f32 v[8:9], v[32:33], v[10:11]
	v_pk_fma_f32 v[4:5], v[54:55], v[44:45], v[4:5]
	v_lshlrev_b32_e32 v35, 16, v3
	v_lshlrev_b32_e32 v34, 16, v2
	v_pk_fma_f32 v[4:5], v[52:53], v[36:37], v[4:5]
	v_pk_fma_f32 v[8:9], v[16:17], v[42:43], v[8:9]
	v_and_b32_e32 v3, 0xffff0000, v3
	v_and_b32_e32 v2, 0xffff0000, v2
	v_pk_fma_f32 v[4:5], v[58:59], v[34:35], v[4:5]
	v_pk_fma_f32 v[8:9], v[20:21], v[6:7], v[8:9]
	v_pk_add_f32 v[4:5], v[4:5], v[60:61]
	v_pk_fma_f32 v[8:9], v[24:25], v[2:3], v[8:9]
	v_and_b32_sdwa v12, v5, v95 dst_sel:DWORD dst_unused:UNUSED_PAD src0_sel:WORD_1 src1_sel:DWORD
	v_pk_add_f32 v[8:9], v[8:9], v[28:29]
	v_and_b32_sdwa v13, v4, v95 dst_sel:DWORD dst_unused:UNUSED_PAD src0_sel:WORD_1 src1_sel:DWORD
	v_add3_u32 v4, v4, v13, s39
	v_add3_u32 v5, v5, v12, s39
	v_and_b32_sdwa v12, v9, v95 dst_sel:DWORD dst_unused:UNUSED_PAD src0_sel:WORD_1 src1_sel:DWORD
	v_and_b32_sdwa v13, v8, v95 dst_sel:DWORD dst_unused:UNUSED_PAD src0_sel:WORD_1 src1_sel:DWORD
	v_add3_u32 v9, v9, v12, s39
	v_add3_u32 v8, v8, v13, s39
	v_and_b32_e32 v9, 0xffff0000, v9
	v_and_b32_e32 v8, 0xffff0000, v8
	v_or_b32_sdwa v5, v9, v5 dst_sel:DWORD dst_unused:UNUSED_PAD src0_sel:DWORD src1_sel:WORD_1
	v_or_b32_sdwa v4, v8, v4 dst_sel:DWORD dst_unused:UNUSED_PAD src0_sel:DWORD src1_sel:WORD_1
	global_store_dwordx2 v[40:41], v[4:5], off
	s_cbranch_vccnz .LBB0_384
; DEVI void mixab_row4(const Params& P, int l, int base, int lt0, int tid) {
;     ...
;     if (t0 + 4 == T) {
;       float* cbp = ti.sample ? P.out + OUT_CBS + (long)(l * 8 + ti.seq) * 3 * 1024 + c : P.out + OUT_CBP + (long)(l * 4 + ti.seq) * 3 * 1024 + c;
; #pragma unroll
;       for (int r = 0; r < 3; ++r)
;         *reinterpret_cast<float4*>(cbp + r * 1024) = make_float4(xk[r + 4][0], xk[r + 4][1], xk[r + 4][2], xk[r + 4][3]);
;     }
	s_add_i32 s24, s24, s44
	s_and_b64 s[26:27], s[26:27], exec
	s_mov_b32 s26, 0x4110000
	s_cselect_b32 s26, s26, 0x4550000
	s_cselect_b32 s24, s24, s46
	s_add_u32 s26, s28, s26
	s_addc_u32 s27, s29, 0
	s_mul_hi_i32 s42, s24, 0x3000
	s_mulk_i32 s24, 0x3000
	s_add_u32 s26, s26, s24
	s_addc_u32 s27, s27, s42
	v_lshl_add_u64 v[12:13], v[100:101], 2, s[26:27]
	v_mov_b32_e32 v8, v0
	v_add_co_u32_e32 v0, vcc, 0x1000, v12
	v_mov_b32_e32 v9, v10
	v_mov_b32_e32 v10, v1
	v_mov_b32_e32 v4, v36
	v_mov_b32_e32 v5, v6
	v_mov_b32_e32 v6, v37
	v_addc_co_u32_e32 v1, vcc, 0, v13, vcc
	global_store_dwordx4 v[0:1], v[4:7], off
	v_mov_b32_e32 v0, v34
	v_mov_b32_e32 v1, v2
	v_add_co_u32_e32 v4, vcc, 0x2000, v12
	v_mov_b32_e32 v2, v35
	s_nop 0
	v_addc_co_u32_e32 v5, vcc, 0, v13, vcc
	global_store_dwordx4 v[12:13], v[8:11], off
	global_store_dwordx4 v[4:5], v[0:3], off
